# ticket hand-off through plain LDS; indexer head weights via 4 broadcast loads
# speedup vs baseline: 1.0010x; 1.0010x over previous
.LBB0_407:
	s_or_b64 exec, exec, s[0:1]
	s_cmp_lg_u32 s86, -1
	s_cselect_b32 s0, s86, 0
	s_cselect_b32 s1, s5, 0
	v_mov_b32_e32 v0, s0
	v_mov_b32_e32 v1, s1
	s_waitcnt lgkmcnt(0)
	s_barrier
	ds_read_b32 v0, v0
	s_waitcnt lgkmcnt(0)
	v_readfirstlane_b32 s36, v0
	s_cmpk_lt_i32 s36, 0x804
	s_cbranch_scc0 .LBB0_799

.LBB0_412:
	s_or_b64 exec, exec, s[0:1]
	s_lshl_b32 s0, s36, 2
	s_sub_i32 s38, 0x200c, s0
	s_sub_i32 s80, 0x210c, s0
	s_cmpk_gt_u32 s80, 0xff
	s_cselect_b64 s[0:1], -1, 0
	s_lshr_b32 s81, s80, 8
	v_mov_b32_e32 v172, v184
	s_cmpk_lt_u32 s80, 0x100
	s_cbranch_scc1 .LBB0_439
	v_readlane_b32 s36, v250, 46
	s_ashr_i32 s39, s38, 31
	v_ashrrev_i32_e32 v0, 5, v172
	v_lshlrev_b32_e32 v168, 3, v172
	v_readlane_b32 s37, v250, 47
	s_lshl_b64 s[48:49], s[38:39], 14
	v_ashrrev_i32_e32 v1, 31, v0
	v_lshl_add_u64 v[96:97], v[168:169], 1, s[36:37]
	s_add_u32 s36, s50, s48
	s_addc_u32 s37, s51, s49
	v_lshlrev_b64 v[2:3], 1, v[0:1]
	v_lshl_add_u64 v[4:5], s[36:37], 0, v[2:3]
	s_or_b32 s36, s38, 1
	s_ashr_i32 s37, s36, 31
	s_lshl_b64 s[44:45], s[36:37], 14
	s_add_u32 s36, s50, s44
	s_addc_u32 s37, s51, s45
	v_lshl_add_u64 v[6:7], s[36:37], 0, v[2:3]
	s_or_b32 s36, s38, 2
	s_ashr_i32 s37, s36, 31
	s_lshl_b64 s[46:47], s[36:37], 14
	s_add_u32 s36, s50, s46
	s_addc_u32 s37, s51, s47
	v_lshl_add_u64 v[8:9], s[36:37], 0, v[2:3]
	s_or_b32 s36, s38, 3
	s_ashr_i32 s37, s36, 31
	s_lshl_b64 s[42:43], s[36:37], 14
	s_movk_i32 s15, 0x1000
	s_add_u32 s36, s50, s42
	v_add_co_u32_e32 v6, vcc, s15, v6
	s_addc_u32 s37, s51, s43
	s_nop 0
	v_addc_co_u32_e32 v7, vcc, 0, v7, vcc
	v_lshl_add_u64 v[10:11], s[36:37], 0, v[2:3]
	v_add_co_u32_e32 v10, vcc, s15, v10
	v_readlane_b32 s39, v250, 54
	s_nop 0
	v_addc_co_u32_e32 v11, vcc, 0, v11, vcc
	s_add_u32 s36, s39, s48
	v_readlane_b32 s58, v250, 55
	s_addc_u32 s37, s58, s49
	v_add_co_u32_e32 v4, vcc, s15, v4
	v_lshl_add_u64 v[12:13], s[36:37], 0, v[2:3]
	s_nop 0
	v_addc_co_u32_e32 v5, vcc, 0, v5, vcc
	s_add_u32 s36, s39, s44
	v_add_co_u32_e32 v12, vcc, s15, v12
	s_addc_u32 s37, s58, s45
	s_nop 0
	v_addc_co_u32_e32 v13, vcc, 0, v13, vcc
	v_lshl_add_u64 v[14:15], s[36:37], 0, v[2:3]
	v_add_co_u32_e32 v14, vcc, s15, v14
	s_add_u32 s36, s39, s46
	s_nop 0
	v_addc_co_u32_e32 v15, vcc, 0, v15, vcc
	s_addc_u32 s37, s58, s47
	v_add_co_u32_e32 v8, vcc, s15, v8
	v_lshl_add_u64 v[16:17], s[36:37], 0, v[2:3]
	s_nop 0
	v_addc_co_u32_e32 v9, vcc, 0, v9, vcc
	s_add_u32 s36, s39, s42
	v_add_co_u32_e32 v16, vcc, s15, v16
	s_addc_u32 s37, s58, s43
	v_readlane_b32 s39, v250, 56
	v_addc_co_u32_e32 v17, vcc, 0, v17, vcc
	v_lshl_add_u64 v[18:19], s[36:37], 0, v[2:3]
	s_add_u32 s36, s39, s48
	v_readlane_b32 s58, v250, 57
	v_add_co_u32_e32 v18, vcc, s15, v18
	s_addc_u32 s37, s58, s49
	s_nop 0
	v_addc_co_u32_e32 v19, vcc, 0, v19, vcc
	v_mov_b32_e32 v241, 0x1680
	s_add_u32 s100, s50, s48
	s_addc_u32 s101, s51, s49
	global_load_dwordx4 v[224:227], v241, s[100:101]
	s_add_u32 s100, s50, s44
	s_addc_u32 s101, s51, s45
	global_load_dwordx4 v[228:231], v241, s[100:101]
	s_add_u32 s100, s50, s46
	s_addc_u32 s101, s51, s47
	global_load_dwordx4 v[232:235], v241, s[100:101]
	s_add_u32 s100, s50, s42
	s_addc_u32 s101, s51, s43
	global_load_dwordx4 v[236:239], v241, s[100:101]
	v_lshl_add_u64 v[4:5], s[36:37], 0, v[2:3]
	s_add_u32 s36, s39, s44
	s_addc_u32 s37, s58, s45
	v_lshl_add_u64 v[6:7], s[36:37], 0, v[2:3]
	s_add_u32 s36, s39, s46
	s_addc_u32 s37, s58, s47
	v_lshl_add_u64 v[8:9], s[36:37], 0, v[2:3]
	s_add_u32 s36, s39, s42
	v_add_co_u32_e32 v6, vcc, s15, v6
	s_addc_u32 s37, s58, s43
	s_nop 0
	v_addc_co_u32_e32 v7, vcc, 0, v7, vcc
	v_lshl_add_u64 v[10:11], s[36:37], 0, v[2:3]
	v_add_co_u32_e32 v10, vcc, s15, v10
	v_readlane_b32 s39, v250, 58
	s_nop 0
	v_addc_co_u32_e32 v11, vcc, 0, v11, vcc
	s_add_u32 s36, s39, s48
	v_readlane_b32 s48, v250, 59
	s_addc_u32 s37, s48, s49
	v_add_co_u32_e32 v4, vcc, s15, v4
	v_lshl_add_u64 v[12:13], s[36:37], 0, v[2:3]
	s_nop 0
	v_addc_co_u32_e32 v5, vcc, 0, v5, vcc
	s_add_u32 s36, s39, s44
	v_add_co_u32_e32 v12, vcc, s15, v12
	s_addc_u32 s37, s48, s45
	s_nop 0
	v_addc_co_u32_e32 v13, vcc, 0, v13, vcc
	v_lshl_add_u64 v[14:15], s[36:37], 0, v[2:3]
	v_add_co_u32_e32 v14, vcc, s15, v14
	s_add_u32 s36, s39, s46
	s_nop 0
	v_addc_co_u32_e32 v15, vcc, 0, v15, vcc
	s_addc_u32 s37, s48, s47
	v_add_co_u32_e32 v8, vcc, s15, v8
	v_lshl_add_u64 v[16:17], s[36:37], 0, v[2:3]
	s_nop 0
	v_addc_co_u32_e32 v9, vcc, 0, v9, vcc
	s_add_u32 s36, s39, s42
	v_add_co_u32_e32 v16, vcc, s15, v16
	s_addc_u32 s37, s48, s43
	s_nop 0
	v_addc_co_u32_e32 v17, vcc, 0, v17, vcc
	v_lshl_add_u64 v[2:3], s[36:37], 0, v[2:3]
	v_add_co_u32_e32 v2, vcc, s15, v2
	v_and_or_b32 v168, v172, 3, s38
	s_nop 0
	v_addc_co_u32_e32 v3, vcc, 0, v3, vcc
	v_lshlrev_b64 v[2:3], 14, v[168:169]
	v_lshlrev_b32_e32 v4, 5, v172
	s_add_i32 s39, s81, 0x7ffffff
	v_lshl_add_u64 v[2:3], s[50:51], 0, v[2:3]
	v_and_b32_e32 v168, 0x380, v4
	v_lshlrev_b32_e32 v4, 3, v0
	v_lshl_add_u64 v[2:3], v[2:3], 0, v[168:169]
	v_ashrrev_i32_e32 v5, 31, v4
	s_lshl_b32 s44, s39, 5
	v_lshl_add_u64 v[2:3], v[4:5], 1, v[2:3]
	s_mov_b64 s[36:37], 0x1200
	s_cmpk_lt_u32 s80, 0x300
	v_lshl_add_u64 v[4:5], v[2:3], 0, s[36:37]
	s_cselect_b32 s36, s44, 64
	s_add_i32 s36, s36, s76
	s_or_b32 s42, s36, 3
	v_add_co_u32_e32 v2, vcc, s15, v2
	s_ashr_i32 s43, s42, 31
	s_nop 0
	v_addc_co_u32_e32 v3, vcc, 0, v3, vcc
	s_lshl_b64 s[42:43], s[42:43], 10
	global_load_dwordx4 v[16:19], v[4:5], off offset:64
	global_load_dwordx4 v[20:23], v[4:5], off offset:32
	global_load_dwordx4 v[24:27], v[4:5], off offset:96
	global_load_dwordx4 v[28:31], v[2:3], off offset:512
	v_lshl_add_u64 v[2:3], v[96:97], 0, s[42:43]
	s_or_b32 s42, s36, 2
	s_ashr_i32 s43, s42, 31
	s_lshl_b64 s[42:43], s[42:43], 10
	v_lshl_add_u64 v[4:5], v[96:97], 0, s[42:43]
	s_or_b32 s42, s36, 1
	s_ashr_i32 s43, s42, 31
	s_ashr_i32 s37, s36, 31
	s_lshl_b64 s[42:43], s[42:43], 10
	s_lshl_b64 s[36:37], s[36:37], 10
	s_cmpk_lt_u32 s80, 0x200
	global_load_dwordx4 v[48:51], v[2:3], off
	global_load_dwordx4 v[52:55], v[4:5], off
	v_lshl_add_u64 v[4:5], v[96:97], 0, s[36:37]
	s_cselect_b32 s36, s44, 32
	s_add_i32 s36, s36, s76
	v_lshl_add_u64 v[2:3], v[96:97], 0, s[42:43]
	s_or_b32 s42, s36, 3
	s_ashr_i32 s43, s42, 31
	s_lshl_b64 s[42:43], s[42:43], 10
	global_load_dwordx4 v[56:59], v[2:3], off
	global_load_dwordx4 v[60:63], v[4:5], off
	v_lshl_add_u64 v[2:3], v[96:97], 0, s[42:43]
	s_or_b32 s42, s36, 2
	s_ashr_i32 s43, s42, 31
	s_lshl_b64 s[42:43], s[42:43], 10
	v_lshl_add_u64 v[4:5], v[96:97], 0, s[42:43]
	s_or_b32 s42, s36, 1
	s_ashr_i32 s37, s36, 31
	s_ashr_i32 s43, s42, 31
	s_lshl_b64 s[36:37], s[36:37], 10
	global_load_dwordx4 v[64:67], v[2:3], off
	global_load_dwordx4 v[68:71], v[4:5], off
	s_lshl_b64 s[42:43], s[42:43], 10
	v_lshl_add_u64 v[4:5], v[96:97], 0, s[36:37]
	v_readlane_b32 s36, v251, 50
	v_lshl_add_u64 v[2:3], v[96:97], 0, s[42:43]
	v_readlane_b32 s37, v251, 51
	global_load_dwordx4 v[72:75], v[2:3], off
	global_load_dwordx4 v[76:79], v[4:5], off
	v_lshl_add_u64 v[2:3], v[96:97], 0, s[36:37]
	v_lshl_add_u64 v[4:5], v[96:97], 0, s[6:7]
	global_load_dwordx4 v[40:43], v[2:3], off
	global_load_dwordx4 v[44:47], v[4:5], off
	v_lshl_add_u64 v[2:3], v[96:97], 0, s[10:11]
	v_lshl_add_u64 v[4:5], v[96:97], 0, s[12:13]
	global_load_dwordx4 v[32:35], v[2:3], off
	global_load_dwordx4 v[36:39], v[4:5], off
	v_lshrrev_b32_e32 v240, 5, v172
	v_sub_u32_e32 v240, 1, v240
	v_lshlrev_b32_e32 v240, 4, v240
	s_waitcnt vmcnt(16)
	v_lshlrev_b32_e32 v242, v240, v224
	v_and_b32_e32 v98, 0xffff0000, v242
	v_lshlrev_b32_e32 v242, v240, v228
	v_and_b32_e32 v106, 0xffff0000, v242
	v_lshlrev_b32_e32 v242, v240, v232
	v_and_b32_e32 v100, 0xffff0000, v242
	v_lshlrev_b32_e32 v242, v240, v236
	v_and_b32_e32 v107, 0xffff0000, v242
	v_lshlrev_b32_e32 v242, v240, v225
	v_and_b32_e32 v99, 0xffff0000, v242
	v_lshlrev_b32_e32 v242, v240, v229
	v_and_b32_e32 v108, 0xffff0000, v242
	v_lshlrev_b32_e32 v242, v240, v233
	v_and_b32_e32 v101, 0xffff0000, v242
	v_lshlrev_b32_e32 v242, v240, v237
	v_and_b32_e32 v109, 0xffff0000, v242
	v_lshlrev_b32_e32 v242, v240, v226
	v_and_b32_e32 v102, 0xffff0000, v242
	v_lshlrev_b32_e32 v242, v240, v230
	v_and_b32_e32 v110, 0xffff0000, v242
	v_lshlrev_b32_e32 v242, v240, v234
	v_and_b32_e32 v104, 0xffff0000, v242
	v_lshlrev_b32_e32 v242, v240, v238
	v_and_b32_e32 v111, 0xffff0000, v242
	v_lshlrev_b32_e32 v242, v240, v227
	v_and_b32_e32 v103, 0xffff0000, v242
	v_lshlrev_b32_e32 v242, v240, v231
	v_and_b32_e32 v112, 0xffff0000, v242
	v_lshlrev_b32_e32 v242, v240, v235
	v_and_b32_e32 v105, 0xffff0000, v242
	v_lshlrev_b32_e32 v242, v240, v239
	v_and_b32_e32 v113, 0xffff0000, v242
	v_lshlrev_b32_e32 v1, 1, v0
	s_mov_b32 s36, 0x10800
	v_and_b32_e32 v2, 31, v172
	v_mul_lo_u32 v3, v0, s36
	v_lshl_add_u32 v115, v0, 13, s17
	v_or_b32_e32 v0, 1, v1
	v_add_u32_e32 v116, s38, v0
	v_lshl_add_u32 v117, v0, 12, s17
	v_lshl_or_b32 v0, v2, 2, v3
	v_add_u32_e32 v114, s38, v1
	v_add_u32_e32 v118, s4, v2
	v_add_u32_e32 v119, s14, v0
	s_mov_b32 s46, 6
	s_branch .LBB0_416

.LBB0_517:
	s_or_b64 exec, exec, s[0:1]
	v_readlane_b32 s0, v250, 36
	v_readlane_b32 s1, v250, 37
	s_and_b64 s[36:37], s[0:1], s[44:45]
	s_and_saveexec_b64 s[0:1], s[36:37]
	s_cbranch_execz .LBB0_407
	s_cmp_lg_u32 s86, -1
	s_cselect_b32 s36, s86, 0
	s_cselect_b32 s37, s5, 0
	v_mov_b32_e32 v0, s36
	v_mov_b32_e32 v1, s37
	s_waitcnt vmcnt(0)
	ds_write_b32 v0, v196
	s_waitcnt lgkmcnt(0)
	s_branch .LBB0_407
